# attention unit queue reordered so 16 WGs per XCD run C,C,C+short units and 16 run B,B,B,B (balances the long-unit tail)
# speedup vs baseline: 1.0036x; 1.0036x over previous
.Lspec_redo_entry:
	s_mov_b32 s99, s12
	s_cmp_lt_i32 s12, 16
	s_mov_b32 s2, s18
	s_cbranch_scc1 .LBB0_96
	s_cmpk_lt_u32 s12, 48
	s_mov_b32 s2, s0
	s_cbranch_scc1 .LBB0_96
	s_add_i32 s2, s35, 32
	s_cmpk_lt_u32 s12, 64
	s_cbranch_scc1 .LBB0_96
	s_add_i32 s2, s0, -16
	s_cmpk_lt_u32 s12, 80
	s_cbranch_scc1 .LBB0_96
	s_add_i32 s2, s35, 16
	s_cmpk_lt_u32 s12, 96
	s_cbranch_scc1 .LBB0_96
	s_add_i32 s2, s0, -32
	s_cmpk_lt_u32 s12, 0x70
	s_cbranch_scc1 .LBB0_96
	s_cmpk_lt_u32 s12, 0xa0
	s_cselect_b32 s2, s34, s19
